# grid barrier: all waiters poll the cross-XCD arrival counter against the round target, release-generation atomic hop removed
# baseline (speedup 1.0000x reference)
; __device__ __forceinline__ unsigned xb_ld(unsigned* p)              { return __hip_atomic_load(p, __ATOMIC_RELAXED, __HIP_MEMORY_SCOPE_AGENT); }
; __device__ __forceinline__ unsigned xb_add(unsigned* p, unsigned v) { return __hip_atomic_fetch_add(p, v, __ATOMIC_RELAXED, __HIP_MEMORY_SCOPE_AGENT); }
; #define XB_SPIN(cond, bar) do { unsigned _sp = 0; while (cond) { __builtin_amdgcn_s_sleep(1); \
;     if ((++_sp & 255u) == 0u) { if (xb_ld(&(bar)[XB_TMO])) break; if (_sp > XB_SPIN_CAP) { atomicAdd(&(bar)[XB_TMO], 1u); break; } } } } while (0)
; __device__ __forceinline__ void xcd_barrier(const XcdBarrier& b) {
;     ...
;         const unsigned old = xb_add(&bar[XB_XSUB(b.x)], 1u);
;         const unsigned gen = old / nloc;
;         if (old + 1u == (gen + 1u) * nloc) {
;             __builtin_amdgcn_fence(__ATOMIC_RELEASE, "agent");
;             asm volatile("s_waitcnt vmcnt(0)" ::: "memory");
;             const unsigned og = xb_add(&bar[XB_TOP], 1u);
;             const unsigned tg = og / nx;
;             if (og + 1u == (tg + 1u) * nx) xb_add(&bar[XB_TOPGEN], 1u);
;             else XB_SPIN(xb_ld(&bar[XB_TOPGEN]) == tg, bar);
;             __builtin_amdgcn_fence(__ATOMIC_ACQUIRE, "agent");
;             xb_add(&bar[XB_XGEN(b.x)], 1u);
;             asm volatile("s_waitcnt vmcnt(0)" ::: "memory");
;         } else {
;             XB_SPIN(xb_ld(&bar[XB_XGEN(b.x)]) == gen, bar);
.LBB0_693:
	v_readlane_b32 s4, v254, 47
	v_readlane_b32 s5, v254, 48
	v_cvt_f32_u32_e32 v1, v2
	v_sub_u32_e32 v5, 0, v2
	v_rcp_iflag_f32_e32 v1, v1
	s_nop 1
	global_atomic_add v4, v3, v213, s[4:5] sc0
	v_mul_f32_e32 v1, 0x4f7ffffe, v1
	v_cvt_u32_f32_e32 v1, v1
	v_mul_lo_u32 v5, v5, v1
	v_mul_hi_u32 v5, v1, v5
	v_add_u32_e32 v1, v1, v5
	s_waitcnt vmcnt(0)
	v_mul_hi_u32 v1, v4, v1
	v_mul_lo_u32 v5, v1, v2
	v_sub_u32_e32 v5, v4, v5
	v_add_u32_e32 v6, 1, v1
	v_cmp_ge_u32_e32 vcc, v5, v2
	v_add_u32_e32 v4, 1, v4
	s_nop 0
	v_cndmask_b32_e32 v1, v1, v6, vcc
	v_sub_u32_e32 v6, v5, v2
	v_cndmask_b32_e32 v5, v5, v6, vcc
	v_add_u32_e32 v6, 1, v1
	v_cmp_ge_u32_e32 vcc, v5, v2
	s_nop 1
	v_cndmask_b32_e32 v1, v1, v6, vcc
	v_mul_lo_u32 v5, v2, v1
	v_add_u32_e32 v2, v5, v2
	v_cmp_ne_u32_e32 vcc, v4, v2
	s_and_saveexec_b64 s[4:5], vcc
	s_xor_b64 s[22:23], exec, s[4:5]
	s_cbranch_execz .LBB0_707
	v_readlane_b32 s4, v254, 51
	v_readlane_b32 s5, v254, 52
	s_waitcnt lgkmcnt(0)
	v_mad_u32_u24 v1, v1, v0, v0
	s_nop 2
	global_load_dword v0, v3, s[4:5] sc1
	s_waitcnt vmcnt(0)
	v_cmp_lt_u32_e32 vcc, v0, v1
	s_and_saveexec_b64 s[24:25], vcc
	s_cbranch_execz .LBB0_706
	s_mov_b32 s4, 1
	s_mov_b64 s[26:27], 0
	s_branch .LBB0_697

; __device__ __forceinline__ unsigned xb_ld(unsigned* p)              { return __hip_atomic_load(p, __ATOMIC_RELAXED, __HIP_MEMORY_SCOPE_AGENT); }
; #define XB_SPIN(cond, bar) do { unsigned _sp = 0; while (cond) { __builtin_amdgcn_s_sleep(1); \
;     if ((++_sp & 255u) == 0u) { if (xb_ld(&(bar)[XB_TMO])) break; if (_sp > XB_SPIN_CAP) { atomicAdd(&(bar)[XB_TMO], 1u); break; } } } } while (0)
; __device__ __forceinline__ void xcd_barrier(const XcdBarrier& b) {
;     ...
;             XB_SPIN(xb_ld(&bar[XB_XGEN(b.x)]) == gen, bar);
.LBB0_701:
	v_readlane_b32 s18, v254, 51
	v_readlane_b32 s19, v254, 52
	s_add_i32 s4, s4, 1
	s_mov_b64 s[38:39], -1
	s_nop 2
	global_load_dword v0, v3, s[18:19] sc1
	s_waitcnt vmcnt(0)
	v_cmp_ge_u32_e32 vcc, v0, v1
	s_orn2_b64 s[36:37], vcc, exec
	s_branch .LBB0_696

; __device__ __forceinline__ unsigned xb_ld(unsigned* p)              { return __hip_atomic_load(p, __ATOMIC_RELAXED, __HIP_MEMORY_SCOPE_AGENT); }
; __device__ __forceinline__ unsigned xb_add(unsigned* p, unsigned v) { return __hip_atomic_fetch_add(p, v, __ATOMIC_RELAXED, __HIP_MEMORY_SCOPE_AGENT); }
; #define XB_SPIN(cond, bar) do { unsigned _sp = 0; while (cond) { __builtin_amdgcn_s_sleep(1); \
;     if ((++_sp & 255u) == 0u) { if (xb_ld(&(bar)[XB_TMO])) break; if (_sp > XB_SPIN_CAP) { atomicAdd(&(bar)[XB_TMO], 1u); break; } } } } while (0)
; __device__ __forceinline__ void xcd_barrier(const XcdBarrier& b) {
;     ...
;             const unsigned og = xb_add(&bar[XB_TOP], 1u);
;             const unsigned tg = og / nx;
;             if (og + 1u == (tg + 1u) * nx) xb_add(&bar[XB_TOPGEN], 1u);
;             else XB_SPIN(xb_ld(&bar[XB_TOPGEN]) == tg, bar);
.LBB0_710:
	s_or_b64 exec, exec, s[24:25]
	s_waitcnt vmcnt(0)
	v_readfirstlane_b32 s4, v2
	v_cvt_f32_u32_e32 v2, v0
	v_sub_u32_e32 v4, 0, v0
	v_add_u32_e32 v1, s4, v1
	v_readlane_b32 s4, v254, 53
	v_rcp_iflag_f32_e32 v2, v2
	v_readlane_b32 s5, v254, 54
	s_mov_b64 s[24:25], 0
	v_mul_f32_e32 v2, 0x4f7ffffe, v2
	v_cvt_u32_f32_e32 v2, v2
	v_mul_lo_u32 v4, v4, v2
	v_mul_hi_u32 v4, v2, v4
	v_add_u32_e32 v2, v2, v4
	v_mul_hi_u32 v2, v1, v2
	v_mul_lo_u32 v4, v2, v0
	v_sub_u32_e32 v4, v1, v4
	v_cmp_ge_u32_e32 vcc, v4, v0
	v_add_u32_e32 v5, 1, v2
	v_add_u32_e32 v1, 1, v1
	v_cndmask_b32_e32 v2, v2, v5, vcc
	v_sub_u32_e32 v5, v4, v0
	v_cndmask_b32_e32 v4, v4, v5, vcc
	v_cmp_ge_u32_e32 vcc, v4, v0
	v_add_u32_e32 v4, 1, v2
	s_nop 0
	v_cndmask_b32_e32 v2, v2, v4, vcc
	v_mul_lo_u32 v4, v0, v2
	v_add_u32_e32 v0, v4, v0
	v_cmp_ne_u32_e32 vcc, v1, v0
	v_mov_b32_e32 v2, v0
	v_mov_b64_e32 v[0:1], s[4:5]
	s_and_saveexec_b64 s[22:23], vcc
	s_cbranch_execz .LBB0_726
	v_readlane_b32 s4, v254, 51
	v_readlane_b32 s5, v254, 52
	s_mov_b64 s[26:27], 0
	s_nop 3
	global_load_dword v0, v3, s[4:5] sc1
	s_waitcnt vmcnt(0)
	v_cmp_lt_u32_e32 vcc, v0, v2
	s_and_saveexec_b64 s[24:25], vcc
	s_cbranch_execz .LBB0_725
	s_mov_b32 s4, 1
	s_branch .LBB0_714

; __device__ __forceinline__ unsigned xb_ld(unsigned* p)              { return __hip_atomic_load(p, __ATOMIC_RELAXED, __HIP_MEMORY_SCOPE_AGENT); }
; #define XB_SPIN(cond, bar) do { unsigned _sp = 0; while (cond) { __builtin_amdgcn_s_sleep(1); \
;     if ((++_sp & 255u) == 0u) { if (xb_ld(&(bar)[XB_TMO])) break; if (_sp > XB_SPIN_CAP) { atomicAdd(&(bar)[XB_TMO], 1u); break; } } } } while (0)
; __device__ __forceinline__ void xcd_barrier(const XcdBarrier& b) {
;     ...
;             else XB_SPIN(xb_ld(&bar[XB_TOPGEN]) == tg, bar);
.LBB0_718:
	v_readlane_b32 s18, v254, 51
	v_readlane_b32 s19, v254, 52
	s_add_i32 s4, s4, 1
	s_mov_b64 s[38:39], -1
	s_nop 2
	global_load_dword v0, v3, s[18:19] sc1
	s_waitcnt vmcnt(0)
	v_cmp_ge_u32_e32 vcc, v0, v2
	s_orn2_b64 s[36:37], vcc, exec
	s_branch .LBB0_713
